# v5 (aligned) plus removal of 128 dead zero v_movs ahead of row_ror DPP movs in the P8 epilogue (hazard pads kept)
# speedup vs baseline: 1.0042x; 1.0038x over previous
.LBB0_1497:
	s_or_b64 exec, exec, s[10:11]
	s_nop 3
	s_waitcnt vmcnt(0) lgkmcnt(0)
	v_mov_b32_dpp v206, v166 row_ror:1 row_mask:0xf bank_mask:0xf
	v_mov_b32_dpp v208, v166 row_ror:2 row_mask:0xf bank_mask:0xf
	v_mov_b32_dpp v207, v167 row_ror:1 row_mask:0xf bank_mask:0xf
	v_mov_b32_dpp v209, v167 row_ror:2 row_mask:0xf bank_mask:0xf
	v_mov_b32_dpp v210, v168 row_ror:2 row_mask:0xf bank_mask:0xf
	v_mov_b32_dpp v211, v169 row_ror:2 row_mask:0xf bank_mask:0xf
	v_mov_b32_dpp v166, v168 row_ror:1 row_mask:0xf bank_mask:0xf
	v_mov_b32_dpp v210, v150 row_shr:2 row_mask:0xf bank_mask:0xf
	v_mov_b32_dpp v167, v169 row_ror:1 row_mask:0xf bank_mask:0xf
	v_mov_b32_dpp v211, v151 row_shr:2 row_mask:0xf bank_mask:0xf
	v_mov_b32_dpp v166, v150 row_shr:1 row_mask:0xf bank_mask:0xf
	v_mov_b32_dpp v167, v151 row_shr:1 row_mask:0xf bank_mask:0xf
	v_pk_fma_f32 v[168:169], v[102:103], v[210:211], v[110:111]
	v_mov_b32_dpp v208, v148 row_shr:2 row_mask:0xf bank_mask:0xf
	v_pk_fma_f32 v[166:167], v[106:107], v[166:167], v[168:169]
	v_mov_b32_dpp v209, v149 row_shr:2 row_mask:0xf bank_mask:0xf
	v_pk_fma_f32 v[166:167], v[150:151], v[98:99], v[166:167]
	v_mov_b32_dpp v206, v148 row_shr:1 row_mask:0xf bank_mask:0xf
	v_mul_f32_e32 v157, 0xbfb8aa3b, v167
	v_exp_f32_e32 v157, v157
	v_mul_f32_e32 v196, 0xbfb8aa3b, v166
	v_exp_f32_e32 v196, v196
	v_mov_b32_dpp v207, v149 row_shr:1 row_mask:0xf bank_mask:0xf
	v_add_f32_e32 v157, 1.0, v157
	v_rcp_f32_e32 v157, v157
	v_pk_fma_f32 v[168:169], v[100:101], v[208:209], v[108:109]
	v_lshl_add_u32 v205, s64, 8, v192
	v_pk_fma_f32 v[168:169], v[104:105], v[206:207], v[168:169]
	v_mul_f32_e32 v157, v167, v157
	v_pk_fma_f32 v[168:169], v[148:149], v[96:97], v[168:169]
	v_mul_f32_e32 v157, v161, v157
	v_add_f32_e32 v161, 1.0, v196
	v_mul_f32_e32 v167, 0xbfb8aa3b, v169
	v_rcp_f32_e32 v161, v161
	v_exp_f32_e32 v167, v167
	v_mul_f32_e32 v196, 0xbfb8aa3b, v168
	v_exp_f32_e32 v196, v196
	v_mul_f32_e32 v161, v166, v161
	v_add_f32_e32 v166, 1.0, v167
	v_rcp_f32_e32 v166, v166
	v_add_f32_e32 v167, 1.0, v196
	v_rcp_f32_e32 v167, v167
	v_mul_f32_e32 v160, v160, v161
	v_mul_f32_e32 v161, v169, v166
	v_mul_f32_e32 v159, v159, v161
	v_mul_f32_e32 v161, v168, v167
	v_mul_f32_e32 v158, v158, v161
	v_cvt_pk_bf16_f32 v158, v158, v159
	v_cvt_pk_bf16_f32 v159, v160, v157
	v_mov_b32_dpp v160, v162 row_ror:1 row_mask:0xf bank_mask:0xf
	v_mov_b32_dpp v166, v162 row_ror:2 row_mask:0xf bank_mask:0xf
	v_mov_b32_dpp v161, v163 row_ror:1 row_mask:0xf bank_mask:0xf
	v_mov_b32_dpp v167, v163 row_ror:2 row_mask:0xf bank_mask:0xf
	v_mov_b32_dpp v168, v164 row_ror:2 row_mask:0xf bank_mask:0xf
	v_mov_b32_dpp v169, v165 row_ror:2 row_mask:0xf bank_mask:0xf
	v_mov_b32_dpp v162, v164 row_ror:1 row_mask:0xf bank_mask:0xf
	v_mov_b32_dpp v168, v146 row_shr:2 row_mask:0xf bank_mask:0xf
	v_mov_b32_dpp v163, v165 row_ror:1 row_mask:0xf bank_mask:0xf
	v_mov_b32_dpp v169, v147 row_shr:2 row_mask:0xf bank_mask:0xf
	v_mov_b32_dpp v162, v146 row_shr:1 row_mask:0xf bank_mask:0xf
	v_mov_b32_dpp v163, v147 row_shr:1 row_mask:0xf bank_mask:0xf
	v_pk_fma_f32 v[164:165], v[74:75], v[168:169], v[86:87]
	v_mov_b32_dpp v166, v144 row_shr:2 row_mask:0xf bank_mask:0xf
	v_pk_fma_f32 v[162:163], v[78:79], v[162:163], v[164:165]
	v_mov_b32_dpp v167, v145 row_shr:2 row_mask:0xf bank_mask:0xf
	v_pk_fma_f32 v[162:163], v[146:147], v[70:71], v[162:163]
	v_mov_b32_dpp v160, v144 row_shr:1 row_mask:0xf bank_mask:0xf
	v_mul_f32_e32 v157, 0xbfb8aa3b, v163
	v_exp_f32_e32 v157, v157
	v_mov_b32_dpp v161, v145 row_shr:1 row_mask:0xf bank_mask:0xf
	v_pk_fma_f32 v[164:165], v[72:73], v[166:167], v[84:85]
	v_add_f32_e32 v157, 1.0, v157
	v_pk_fma_f32 v[160:161], v[76:77], v[160:161], v[164:165]
	v_rcp_f32_e32 v157, v157
	v_mul_f32_e32 v164, 0xbfb8aa3b, v162
	v_exp_f32_e32 v164, v164
	v_pk_fma_f32 v[160:161], v[144:145], v[68:69], v[160:161]
	v_mul_f32_e32 v157, v163, v157
	v_mul_f32_e32 v155, v155, v157
	v_add_f32_e32 v157, 1.0, v164
	v_mul_f32_e32 v163, 0xbfb8aa3b, v161
	v_rcp_f32_e32 v157, v157
	v_exp_f32_e32 v163, v163
	v_mul_f32_e32 v164, 0xbfb8aa3b, v160
	v_exp_f32_e32 v164, v164
	v_mul_f32_e32 v157, v162, v157
	v_add_f32_e32 v162, 1.0, v163
	v_rcp_f32_e32 v162, v162
	v_add_f32_e32 v163, 1.0, v164
	v_rcp_f32_e32 v163, v163
	v_mul_f32_e32 v154, v154, v157
	v_mul_f32_e32 v157, v161, v162
	v_mul_f32_e32 v153, v153, v157
	v_mul_f32_e32 v157, v160, v163
	v_mul_f32_e32 v152, v152, v157
	v_cvt_pk_bf16_f32 v160, v152, v153
	v_cvt_pk_bf16_f32 v161, v154, v155
	v_mov_b64_e32 v[154:155], s[18:19]
	v_mad_i64_i32 v[162:163], s[10:11], v205, s82, v[154:155]
	v_lshlrev_b64 v[152:153], 1, v[188:189]
	v_lshl_add_u64 v[162:163], v[162:163], 0, v[152:153]
	global_store_dwordx4 v[162:163], v[158:161], off
	s_nop 1
	v_mov_b32_dpp v158, v148 row_ror:1 row_mask:0xf bank_mask:0xf
	v_mov_b32_dpp v160, v148 row_ror:2 row_mask:0xf bank_mask:0xf
	v_mov_b32_dpp v159, v149 row_ror:1 row_mask:0xf bank_mask:0xf
	v_mov_b32_dpp v161, v149 row_ror:2 row_mask:0xf bank_mask:0xf
	v_mov_b32_dpp v162, v150 row_ror:2 row_mask:0xf bank_mask:0xf
	v_mov_b32_dpp v163, v151 row_ror:2 row_mask:0xf bank_mask:0xf
	v_mov_b32_dpp v148, v150 row_ror:1 row_mask:0xf bank_mask:0xf
	v_mov_b32_dpp v162, v134 row_shr:2 row_mask:0xf bank_mask:0xf
	v_mov_b32_dpp v149, v151 row_ror:1 row_mask:0xf bank_mask:0xf
	v_mov_b32_dpp v163, v135 row_shr:2 row_mask:0xf bank_mask:0xf
	v_mov_b32_dpp v148, v134 row_shr:1 row_mask:0xf bank_mask:0xf
	v_mov_b32_dpp v149, v135 row_shr:1 row_mask:0xf bank_mask:0xf
	v_pk_fma_f32 v[150:151], v[102:103], v[162:163], v[110:111]
	v_mov_b32_dpp v160, v132 row_shr:2 row_mask:0xf bank_mask:0xf
	v_pk_fma_f32 v[148:149], v[106:107], v[148:149], v[150:151]
	v_mov_b32_dpp v161, v133 row_shr:2 row_mask:0xf bank_mask:0xf
	v_pk_fma_f32 v[148:149], v[134:135], v[98:99], v[148:149]
	v_mov_b32_dpp v158, v132 row_shr:1 row_mask:0xf bank_mask:0xf
	v_mul_f32_e32 v150, 0xbfb8aa3b, v149
	v_exp_f32_e32 v157, v150
	v_mov_b32_dpp v159, v133 row_shr:1 row_mask:0xf bank_mask:0xf
	v_pk_fma_f32 v[150:151], v[100:101], v[160:161], v[108:109]
	v_add_f32_e32 v157, 1.0, v157
	v_pk_fma_f32 v[150:151], v[104:105], v[158:159], v[150:151]
	v_rcp_f32_e32 v157, v157
	v_mul_f32_e32 v158, 0xbfb8aa3b, v148
	v_exp_f32_e32 v158, v158
	v_pk_fma_f32 v[150:151], v[132:133], v[96:97], v[150:151]
	v_mul_f32_e32 v149, v149, v157
	v_mul_f32_e32 v143, v143, v149
	v_add_f32_e32 v149, 1.0, v158
	v_mul_f32_e32 v157, 0xbfb8aa3b, v151
	v_rcp_f32_e32 v149, v149
	v_exp_f32_e32 v157, v157
	v_mul_f32_e32 v158, 0xbfb8aa3b, v150
	v_exp_f32_e32 v158, v158
	v_mul_f32_e32 v148, v148, v149
	v_add_f32_e32 v149, 1.0, v157
	v_rcp_f32_e32 v149, v149
	v_add_f32_e32 v157, 1.0, v158
	v_rcp_f32_e32 v157, v157
	v_mul_f32_e32 v142, v142, v148
	v_mul_f32_e32 v148, v151, v149
	v_mul_f32_e32 v141, v141, v148
	v_mul_f32_e32 v148, v150, v157
	v_mul_f32_e32 v140, v140, v148
	v_cvt_pk_bf16_f32 v140, v140, v141
	v_cvt_pk_bf16_f32 v141, v142, v143
	v_mov_b32_dpp v142, v144 row_ror:1 row_mask:0xf bank_mask:0xf
	v_mov_b32_dpp v148, v144 row_ror:2 row_mask:0xf bank_mask:0xf
	v_mov_b32_dpp v143, v145 row_ror:1 row_mask:0xf bank_mask:0xf
	v_mov_b32_dpp v149, v145 row_ror:2 row_mask:0xf bank_mask:0xf
	v_mov_b32_dpp v150, v146 row_ror:2 row_mask:0xf bank_mask:0xf
	v_mov_b32_dpp v151, v147 row_ror:2 row_mask:0xf bank_mask:0xf
	v_mov_b32_dpp v144, v146 row_ror:1 row_mask:0xf bank_mask:0xf
	v_mov_b32_dpp v150, v130 row_shr:2 row_mask:0xf bank_mask:0xf
	v_mov_b32_dpp v145, v147 row_ror:1 row_mask:0xf bank_mask:0xf
	v_mov_b32_dpp v151, v131 row_shr:2 row_mask:0xf bank_mask:0xf
	v_mov_b32_dpp v144, v130 row_shr:1 row_mask:0xf bank_mask:0xf
	v_mov_b32_dpp v145, v131 row_shr:1 row_mask:0xf bank_mask:0xf
	v_pk_fma_f32 v[146:147], v[74:75], v[150:151], v[86:87]
	v_mov_b32_dpp v148, v128 row_shr:2 row_mask:0xf bank_mask:0xf
	v_pk_fma_f32 v[144:145], v[78:79], v[144:145], v[146:147]
	v_mov_b32_dpp v149, v129 row_shr:2 row_mask:0xf bank_mask:0xf
	v_pk_fma_f32 v[144:145], v[130:131], v[70:71], v[144:145]
	v_mov_b32_dpp v142, v128 row_shr:1 row_mask:0xf bank_mask:0xf
	v_mul_f32_e32 v146, 0xbfb8aa3b, v145
	v_exp_f32_e32 v150, v146
	v_mov_b32_dpp v143, v129 row_shr:1 row_mask:0xf bank_mask:0xf
	v_pk_fma_f32 v[146:147], v[72:73], v[148:149], v[84:85]
	v_mov_b32_e32 v157, 0
	v_pk_fma_f32 v[142:143], v[76:77], v[142:143], v[146:147]
	v_add_f32_e32 v146, 1.0, v150
	v_rcp_f32_e32 v146, v146
	v_mul_f32_e32 v147, 0xbfb8aa3b, v144
	v_exp_f32_e32 v147, v147
	v_pk_fma_f32 v[142:143], v[128:129], v[68:69], v[142:143]
	v_mul_f32_e32 v145, v145, v146
	v_mul_f32_e32 v139, v139, v145
	v_add_f32_e32 v145, 1.0, v147
	v_mul_f32_e32 v146, 0xbfb8aa3b, v143
	v_mul_f32_e32 v147, 0xbfb8aa3b, v142
	v_rcp_f32_e32 v145, v145
	v_exp_f32_e32 v146, v146
	v_exp_f32_e32 v147, v147
	v_mov_b32_e32 v158, 0
	v_mul_f32_e32 v144, v144, v145
	v_add_f32_e32 v145, 1.0, v146
	v_add_f32_e32 v146, 1.0, v147
	v_rcp_f32_e32 v146, v146
	v_rcp_f32_e32 v145, v145
	v_mul_f32_e32 v138, v138, v144
	v_mov_b32_e32 v159, 0
	v_mul_f32_e32 v142, v142, v146
	v_mul_f32_e32 v143, v143, v145
	v_mul_f32_e32 v136, v136, v142
	v_mul_f32_e32 v137, v137, v143
	v_cvt_pk_bf16_f32 v142, v136, v137
	v_or_b32_e32 v136, 16, v205
	v_mad_i64_i32 v[136:137], s[10:11], v136, s82, v[154:155]
	v_lshl_add_u64 v[136:137], v[136:137], 0, v[152:153]
	v_cvt_pk_bf16_f32 v143, v138, v139
	global_store_dwordx4 v[136:137], v[140:143], off
	v_mov_b32_dpp v136, v132 row_ror:1 row_mask:0xf bank_mask:0xf
	v_mov_b32_dpp v138, v132 row_ror:2 row_mask:0xf bank_mask:0xf
	v_mov_b32_dpp v137, v133 row_ror:1 row_mask:0xf bank_mask:0xf
	v_mov_b32_dpp v139, v133 row_ror:2 row_mask:0xf bank_mask:0xf
	v_mov_b32_dpp v140, v134 row_ror:2 row_mask:0xf bank_mask:0xf
	v_mov_b32_dpp v141, v135 row_ror:2 row_mask:0xf bank_mask:0xf
	v_mov_b32_dpp v132, v134 row_ror:1 row_mask:0xf bank_mask:0xf
	v_mov_b32_dpp v140, v118 row_shr:2 row_mask:0xf bank_mask:0xf
	v_mov_b32_dpp v133, v135 row_ror:1 row_mask:0xf bank_mask:0xf
	v_mov_b32_dpp v141, v119 row_shr:2 row_mask:0xf bank_mask:0xf
	v_mov_b32_dpp v132, v118 row_shr:1 row_mask:0xf bank_mask:0xf
	v_mov_b32_dpp v133, v119 row_shr:1 row_mask:0xf bank_mask:0xf
	v_pk_fma_f32 v[134:135], v[102:103], v[140:141], v[110:111]
	v_mov_b32_dpp v138, v116 row_shr:2 row_mask:0xf bank_mask:0xf
	v_pk_fma_f32 v[132:133], v[106:107], v[132:133], v[134:135]
	v_mov_b32_dpp v139, v117 row_shr:2 row_mask:0xf bank_mask:0xf
	v_pk_fma_f32 v[132:133], v[118:119], v[98:99], v[132:133]
	v_mov_b32_dpp v136, v116 row_shr:1 row_mask:0xf bank_mask:0xf
	v_mul_f32_e32 v134, 0xbfb8aa3b, v133
	v_exp_f32_e32 v140, v134
	v_mov_b32_dpp v137, v117 row_shr:1 row_mask:0xf bank_mask:0xf
	v_pk_fma_f32 v[134:135], v[100:101], v[138:139], v[108:109]
	s_nop 0
	v_pk_fma_f32 v[134:135], v[104:105], v[136:137], v[134:135]
	v_add_f32_e32 v136, 1.0, v140
	v_rcp_f32_e32 v136, v136
	v_mul_f32_e32 v137, 0xbfb8aa3b, v132
	v_exp_f32_e32 v137, v137
	v_pk_fma_f32 v[134:135], v[116:117], v[96:97], v[134:135]
	v_mul_f32_e32 v133, v133, v136
	v_mul_f32_e32 v127, v127, v133
	v_add_f32_e32 v133, 1.0, v137
	v_mul_f32_e32 v136, 0xbfb8aa3b, v135
	v_rcp_f32_e32 v133, v133
	v_exp_f32_e32 v136, v136
	v_mul_f32_e32 v137, 0xbfb8aa3b, v134
	v_exp_f32_e32 v137, v137
	v_mul_f32_e32 v132, v132, v133
	v_add_f32_e32 v133, 1.0, v136
	v_rcp_f32_e32 v133, v133
	v_add_f32_e32 v136, 1.0, v137
	v_rcp_f32_e32 v136, v136
	v_mul_f32_e32 v126, v126, v132
	v_mul_f32_e32 v132, v135, v133
	v_mul_f32_e32 v125, v125, v132
	v_mul_f32_e32 v132, v134, v136
	v_mul_f32_e32 v124, v124, v132
	v_cvt_pk_bf16_f32 v124, v124, v125
	v_cvt_pk_bf16_f32 v125, v126, v127
	v_mov_b32_dpp v126, v128 row_ror:1 row_mask:0xf bank_mask:0xf
	v_mov_b32_dpp v132, v128 row_ror:2 row_mask:0xf bank_mask:0xf
	v_mov_b32_dpp v127, v129 row_ror:1 row_mask:0xf bank_mask:0xf
	v_mov_b32_dpp v133, v129 row_ror:2 row_mask:0xf bank_mask:0xf
	v_mov_b32_dpp v134, v130 row_ror:2 row_mask:0xf bank_mask:0xf
	v_mov_b32_dpp v135, v131 row_ror:2 row_mask:0xf bank_mask:0xf
	v_mov_b32_dpp v128, v130 row_ror:1 row_mask:0xf bank_mask:0xf
	v_mov_b32_dpp v134, v94 row_shr:2 row_mask:0xf bank_mask:0xf
	v_mov_b32_dpp v129, v131 row_ror:1 row_mask:0xf bank_mask:0xf
	v_mov_b32_dpp v135, v95 row_shr:2 row_mask:0xf bank_mask:0xf
	v_mov_b32_dpp v128, v94 row_shr:1 row_mask:0xf bank_mask:0xf
	v_mov_b32_dpp v129, v95 row_shr:1 row_mask:0xf bank_mask:0xf
	v_pk_fma_f32 v[130:131], v[74:75], v[134:135], v[86:87]
	v_mov_b32_dpp v132, v92 row_shr:2 row_mask:0xf bank_mask:0xf
	v_pk_fma_f32 v[128:129], v[78:79], v[128:129], v[130:131]
	v_mov_b32_dpp v133, v93 row_shr:2 row_mask:0xf bank_mask:0xf
	v_pk_fma_f32 v[128:129], v[94:95], v[70:71], v[128:129]
	v_mov_b32_dpp v126, v92 row_shr:1 row_mask:0xf bank_mask:0xf
	v_mul_f32_e32 v130, 0xbfb8aa3b, v129
	v_exp_f32_e32 v134, v130
	v_mov_b32_dpp v127, v93 row_shr:1 row_mask:0xf bank_mask:0xf
	v_pk_fma_f32 v[130:131], v[72:73], v[132:133], v[84:85]
	s_nop 0
	v_pk_fma_f32 v[126:127], v[76:77], v[126:127], v[130:131]
	v_add_f32_e32 v130, 1.0, v134
	v_rcp_f32_e32 v130, v130
	v_mul_f32_e32 v131, 0xbfb8aa3b, v128
	v_exp_f32_e32 v131, v131
	v_pk_fma_f32 v[126:127], v[92:93], v[68:69], v[126:127]
	v_mul_f32_e32 v129, v129, v130
	v_mul_f32_e32 v123, v123, v129
	v_add_f32_e32 v129, 1.0, v131
	v_mul_f32_e32 v130, 0xbfb8aa3b, v127
	v_mul_f32_e32 v131, 0xbfb8aa3b, v126
	v_rcp_f32_e32 v129, v129
	v_exp_f32_e32 v130, v130
	v_exp_f32_e32 v131, v131
	v_mul_f32_e32 v128, v128, v129
	v_add_f32_e32 v129, 1.0, v130
	v_add_f32_e32 v130, 1.0, v131
	v_rcp_f32_e32 v130, v130
	v_rcp_f32_e32 v129, v129
	v_mul_f32_e32 v122, v122, v128
	v_mul_f32_e32 v126, v126, v130
	v_mul_f32_e32 v127, v127, v129
	v_mul_f32_e32 v120, v120, v126
	v_mul_f32_e32 v121, v121, v127
	v_cvt_pk_bf16_f32 v126, v120, v121
	v_or_b32_e32 v120, 32, v205
	v_mad_i64_i32 v[120:121], s[10:11], v120, s82, v[154:155]
	v_lshl_add_u64 v[120:121], v[120:121], 0, v[152:153]
	v_cvt_pk_bf16_f32 v127, v122, v123
	global_store_dwordx4 v[120:121], v[124:127], off
	v_mov_b32_dpp v120, v116 row_ror:1 row_mask:0xf bank_mask:0xf
	v_mov_b32_dpp v122, v116 row_ror:2 row_mask:0xf bank_mask:0xf
	v_mov_b32_dpp v121, v117 row_ror:1 row_mask:0xf bank_mask:0xf
	v_mov_b32_dpp v123, v117 row_ror:2 row_mask:0xf bank_mask:0xf
	v_mov_b32_dpp v124, v118 row_ror:2 row_mask:0xf bank_mask:0xf
	v_mov_b32_dpp v125, v119 row_ror:2 row_mask:0xf bank_mask:0xf
	v_mov_b32_dpp v116, v118 row_ror:1 row_mask:0xf bank_mask:0xf
	v_mov_b32_dpp v124, v114 row_shr:2 row_mask:0xf bank_mask:0xf
	v_mov_b32_dpp v117, v119 row_ror:1 row_mask:0xf bank_mask:0xf
	v_mov_b32_dpp v125, v115 row_shr:2 row_mask:0xf bank_mask:0xf
	v_mov_b32_dpp v116, v114 row_shr:1 row_mask:0xf bank_mask:0xf
	v_mov_b32_dpp v117, v115 row_shr:1 row_mask:0xf bank_mask:0xf
	v_pk_fma_f32 v[118:119], v[102:103], v[124:125], v[110:111]
	v_mov_b32_dpp v122, v112 row_shr:2 row_mask:0xf bank_mask:0xf
	v_pk_fma_f32 v[116:117], v[106:107], v[116:117], v[118:119]
	v_mov_b32_dpp v123, v113 row_shr:2 row_mask:0xf bank_mask:0xf
	v_pk_fma_f32 v[114:115], v[114:115], v[98:99], v[116:117]
	v_mov_b32_dpp v120, v112 row_shr:1 row_mask:0xf bank_mask:0xf
	v_mul_f32_e32 v116, 0xbfb8aa3b, v115
	v_exp_f32_e32 v118, v116
	v_mul_f32_e32 v119, 0xbfb8aa3b, v114
	v_exp_f32_e32 v119, v119
	v_mov_b32_dpp v121, v113 row_shr:1 row_mask:0xf bank_mask:0xf
	v_add_f32_e32 v118, 1.0, v118
	v_rcp_f32_e32 v118, v118
	v_pk_fma_f32 v[116:117], v[100:101], v[122:123], v[108:109]
	v_mul_f32_e32 v115, v115, v118
	v_pk_fma_f32 v[116:117], v[104:105], v[120:121], v[116:117]
	v_mul_f32_e32 v91, v91, v115
	v_pk_fma_f32 v[112:113], v[112:113], v[96:97], v[116:117]
	v_add_f32_e32 v115, 1.0, v119
	v_mul_f32_e32 v116, 0xbfb8aa3b, v113
	v_mul_f32_e32 v117, 0xbfb8aa3b, v112
	v_rcp_f32_e32 v115, v115
	v_exp_f32_e32 v116, v116
	v_exp_f32_e32 v117, v117
	v_mul_f32_e32 v114, v114, v115
	v_add_f32_e32 v115, 1.0, v116
	v_add_f32_e32 v116, 1.0, v117
	v_rcp_f32_e32 v115, v115
	v_rcp_f32_e32 v116, v116
	v_mul_f32_e32 v90, v90, v114
	v_mul_f32_e32 v113, v113, v115
	v_mul_f32_e32 v112, v112, v116
	v_mul_f32_e32 v89, v89, v113
	v_mul_f32_e32 v88, v88, v112
	v_cvt_pk_bf16_f32 v88, v88, v89
	v_cvt_pk_bf16_f32 v89, v90, v91
	v_mov_b32_dpp v90, v92 row_ror:1 row_mask:0xf bank_mask:0xf
	v_mov_b32_dpp v112, v92 row_ror:2 row_mask:0xf bank_mask:0xf
	v_mov_b32_dpp v91, v93 row_ror:1 row_mask:0xf bank_mask:0xf
	v_mov_b32_dpp v113, v93 row_ror:2 row_mask:0xf bank_mask:0xf
	v_mov_b32_dpp v114, v94 row_ror:2 row_mask:0xf bank_mask:0xf
	v_mov_b32_dpp v115, v95 row_ror:2 row_mask:0xf bank_mask:0xf
	v_mov_b32_dpp v92, v94 row_ror:1 row_mask:0xf bank_mask:0xf
	v_mov_b32_dpp v114, v82 row_shr:2 row_mask:0xf bank_mask:0xf
	v_mov_b32_dpp v93, v95 row_ror:1 row_mask:0xf bank_mask:0xf
	v_mov_b32_dpp v115, v83 row_shr:2 row_mask:0xf bank_mask:0xf
	v_mov_b32_dpp v92, v82 row_shr:1 row_mask:0xf bank_mask:0xf
	v_mov_b32_dpp v93, v83 row_shr:1 row_mask:0xf bank_mask:0xf
	v_pk_fma_f32 v[94:95], v[74:75], v[114:115], v[86:87]
	v_mov_b32_dpp v112, v80 row_shr:2 row_mask:0xf bank_mask:0xf
	v_pk_fma_f32 v[92:93], v[78:79], v[92:93], v[94:95]
	v_mov_b32_dpp v113, v81 row_shr:2 row_mask:0xf bank_mask:0xf
	v_pk_fma_f32 v[82:83], v[82:83], v[70:71], v[92:93]
	v_mov_b32_dpp v90, v80 row_shr:1 row_mask:0xf bank_mask:0xf
	v_mul_f32_e32 v92, 0xbfb8aa3b, v83
	v_exp_f32_e32 v94, v92
	v_mov_b32_dpp v91, v81 row_shr:1 row_mask:0xf bank_mask:0xf
	v_pk_fma_f32 v[92:93], v[72:73], v[112:113], v[84:85]
	s_nop 0
	v_pk_fma_f32 v[90:91], v[76:77], v[90:91], v[92:93]
	v_add_f32_e32 v92, 1.0, v94
	v_rcp_f32_e32 v92, v92
	v_mul_f32_e32 v93, 0xbfb8aa3b, v82
	v_exp_f32_e32 v93, v93
	v_pk_fma_f32 v[80:81], v[80:81], v[68:69], v[90:91]
	v_mul_f32_e32 v83, v83, v92
	v_mul_f32_e32 v67, v67, v83
	v_add_f32_e32 v83, 1.0, v93
	v_mul_f32_e32 v90, 0xbfb8aa3b, v81
	v_mul_f32_e32 v91, 0xbfb8aa3b, v80
	v_rcp_f32_e32 v83, v83
	v_exp_f32_e32 v90, v90
	v_exp_f32_e32 v91, v91
	v_mul_f32_e32 v82, v82, v83
	v_add_f32_e32 v83, 1.0, v90
	v_add_f32_e32 v90, 1.0, v91
	v_rcp_f32_e32 v90, v90
	v_rcp_f32_e32 v83, v83
	v_mul_f32_e32 v66, v66, v82
	v_mul_f32_e32 v80, v80, v90
	v_mul_f32_e32 v81, v81, v83
	v_mul_f32_e32 v64, v64, v80
	v_mul_f32_e32 v65, v65, v81
	v_cvt_pk_bf16_f32 v90, v64, v65
	v_or_b32_e32 v64, 48, v205
	v_mad_i64_i32 v[64:65], s[10:11], v64, s82, v[154:155]
	v_lshl_add_u64 v[64:65], v[64:65], 0, v[152:153]
	v_cvt_pk_bf16_f32 v91, v66, v67
	global_store_dwordx4 v[64:65], v[88:91], off
	v_mov_b32_e32 v64, 0
	v_mov_b32_e32 v65, 0
	v_mov_b32_e32 v66, 0
	v_mov_b32_e32 v67, 0
	s_and_saveexec_b64 s[10:11], s[6:7]
	s_cbranch_execz .LBB0_1501
	s_andn2_b64 vcc, exec, s[54:55]
	s_cbranch_vccnz .LBB0_1511
	ds_read_b128 v[64:67], v201
	ds_read_b128 v[156:159], v201 offset:16
	s_cbranch_execnz .LBB0_1501

.LBB0_1501:
	s_or_b64 exec, exec, s[10:11]
	s_nop 3
	s_waitcnt lgkmcnt(1)
	v_mov_b32_dpp v80, v64 row_ror:1 row_mask:0xf bank_mask:0xf
	v_mov_b32_dpp v82, v64 row_ror:2 row_mask:0xf bank_mask:0xf
	v_mov_b32_dpp v81, v65 row_ror:1 row_mask:0xf bank_mask:0xf
	v_mov_b32_dpp v83, v65 row_ror:2 row_mask:0xf bank_mask:0xf
	v_mov_b32_dpp v88, v66 row_ror:2 row_mask:0xf bank_mask:0xf
	v_mov_b32_dpp v89, v67 row_ror:2 row_mask:0xf bank_mask:0xf
	v_mov_b32_dpp v64, v66 row_ror:1 row_mask:0xf bank_mask:0xf
	v_mov_b32_dpp v88, v54 row_shr:2 row_mask:0xf bank_mask:0xf
	v_mov_b32_dpp v65, v67 row_ror:1 row_mask:0xf bank_mask:0xf
	v_mov_b32_dpp v89, v55 row_shr:2 row_mask:0xf bank_mask:0xf
	v_mov_b32_dpp v64, v54 row_shr:1 row_mask:0xf bank_mask:0xf
	v_mov_b32_dpp v65, v55 row_shr:1 row_mask:0xf bank_mask:0xf
	v_pk_fma_f32 v[66:67], v[102:103], v[88:89], v[110:111]
	v_mov_b32_dpp v82, v52 row_shr:2 row_mask:0xf bank_mask:0xf
	v_pk_fma_f32 v[64:65], v[106:107], v[64:65], v[66:67]
	v_mov_b32_dpp v83, v53 row_shr:2 row_mask:0xf bank_mask:0xf
	v_pk_fma_f32 v[64:65], v[54:55], v[98:99], v[64:65]
	v_mov_b32_dpp v80, v52 row_shr:1 row_mask:0xf bank_mask:0xf
	v_mul_f32_e32 v66, 0xbfb8aa3b, v65
	v_exp_f32_e32 v88, v66
	v_mov_b32_dpp v81, v53 row_shr:1 row_mask:0xf bank_mask:0xf
	v_pk_fma_f32 v[66:67], v[100:101], v[82:83], v[108:109]
	v_add_u32_e32 v90, 0x80, v205
	v_pk_fma_f32 v[66:67], v[104:105], v[80:81], v[66:67]
	v_add_f32_e32 v80, 1.0, v88
	v_rcp_f32_e32 v80, v80
	v_mul_f32_e32 v81, 0xbfb8aa3b, v64
	v_exp_f32_e32 v81, v81
	v_pk_fma_f32 v[66:67], v[52:53], v[96:97], v[66:67]
	v_mul_f32_e32 v65, v65, v80
	v_mul_f32_e32 v63, v63, v65
	v_add_f32_e32 v65, 1.0, v81
	v_mul_f32_e32 v80, 0xbfb8aa3b, v67
	v_rcp_f32_e32 v65, v65
	v_exp_f32_e32 v80, v80
	v_mul_f32_e32 v81, 0xbfb8aa3b, v66
	v_exp_f32_e32 v81, v81
	v_mul_f32_e32 v64, v64, v65
	v_add_f32_e32 v65, 1.0, v80
	v_rcp_f32_e32 v65, v65
	v_add_f32_e32 v80, 1.0, v81
	v_rcp_f32_e32 v80, v80
	v_mul_f32_e32 v62, v62, v64
	v_mul_f32_e32 v64, v67, v65
	v_mul_f32_e32 v61, v61, v64
	v_mul_f32_e32 v64, v66, v80
	s_waitcnt lgkmcnt(0)
	v_mov_b32_dpp v80, v158 row_ror:2 row_mask:0xf bank_mask:0xf
	v_mov_b32_dpp v81, v159 row_ror:2 row_mask:0xf bank_mask:0xf
	v_mov_b32_dpp v66, v158 row_ror:1 row_mask:0xf bank_mask:0xf
	v_mov_b32_dpp v80, v50 row_shr:2 row_mask:0xf bank_mask:0xf
	v_mov_b32_dpp v67, v159 row_ror:1 row_mask:0xf bank_mask:0xf
	v_mov_b32_dpp v81, v51 row_shr:2 row_mask:0xf bank_mask:0xf
	v_mov_b32_dpp v66, v50 row_shr:1 row_mask:0xf bank_mask:0xf
	v_mov_b32_dpp v67, v51 row_shr:1 row_mask:0xf bank_mask:0xf
	v_pk_fma_f32 v[80:81], v[74:75], v[80:81], v[86:87]
	v_mul_f32_e32 v60, v60, v64
	v_pk_fma_f32 v[66:67], v[78:79], v[66:67], v[80:81]
	v_pk_fma_f32 v[66:67], v[50:51], v[70:71], v[66:67]
	v_mul_f32_e32 v80, 0xbfb8aa3b, v67
	v_exp_f32_e32 v80, v80
	v_cvt_pk_bf16_f32 v60, v60, v61
	v_cvt_pk_bf16_f32 v61, v62, v63
	v_mov_b32_dpp v64, v156 row_ror:2 row_mask:0xf bank_mask:0xf
	v_mov_b32_dpp v65, v157 row_ror:2 row_mask:0xf bank_mask:0xf
	v_mov_b32_dpp v62, v156 row_ror:1 row_mask:0xf bank_mask:0xf
	v_mov_b32_dpp v64, v48 row_shr:2 row_mask:0xf bank_mask:0xf
	v_mov_b32_dpp v63, v157 row_ror:1 row_mask:0xf bank_mask:0xf
	v_mov_b32_dpp v65, v49 row_shr:2 row_mask:0xf bank_mask:0xf
	v_mov_b32_dpp v62, v48 row_shr:1 row_mask:0xf bank_mask:0xf
	v_mov_b32_dpp v63, v49 row_shr:1 row_mask:0xf bank_mask:0xf
	v_pk_fma_f32 v[64:65], v[72:73], v[64:65], v[84:85]
	s_andn2_b64 vcc, exec, s[8:9]
	v_pk_fma_f32 v[62:63], v[76:77], v[62:63], v[64:65]
	v_add_f32_e32 v64, 1.0, v80
	v_rcp_f32_e32 v64, v64
	v_mul_f32_e32 v65, 0xbfb8aa3b, v66
	v_exp_f32_e32 v65, v65
	v_pk_fma_f32 v[62:63], v[48:49], v[68:69], v[62:63]
	v_mul_f32_e32 v64, v67, v64
	v_mul_f32_e32 v59, v59, v64
	v_add_f32_e32 v64, 1.0, v65
	v_mul_f32_e32 v65, 0xbfb8aa3b, v63
	v_mul_f32_e32 v67, 0xbfb8aa3b, v62
	v_rcp_f32_e32 v64, v64
	v_exp_f32_e32 v65, v65
	v_exp_f32_e32 v67, v67
	s_mov_b64 s[8:9], -1
	v_mul_f32_e32 v64, v66, v64
	v_add_f32_e32 v65, 1.0, v65
	v_add_f32_e32 v66, 1.0, v67
	v_rcp_f32_e32 v65, v65
	v_rcp_f32_e32 v66, v66
	v_mul_f32_e32 v58, v58, v64
	v_mul_f32_e32 v63, v63, v65
	v_mul_f32_e32 v62, v62, v66
	v_mul_f32_e32 v57, v57, v63
	v_mul_f32_e32 v56, v56, v62
	v_cvt_pk_bf16_f32 v62, v56, v57
	v_mov_b64_e32 v[56:57], s[18:19]
	v_cvt_pk_bf16_f32 v63, v58, v59
	v_mad_i64_i32 v[58:59], s[10:11], v90, s82, v[56:57]
	v_lshl_add_u64 v[58:59], v[58:59], 0, v[152:153]
	global_store_dwordx4 v[58:59], v[60:63], off
	s_nop 1
	v_mov_b32_dpp v58, v52 row_ror:1 row_mask:0xf bank_mask:0xf
	v_mov_b32_dpp v60, v52 row_ror:2 row_mask:0xf bank_mask:0xf
	v_mov_b32_dpp v59, v53 row_ror:1 row_mask:0xf bank_mask:0xf
	v_mov_b32_dpp v61, v53 row_ror:2 row_mask:0xf bank_mask:0xf
	v_mov_b32_dpp v62, v54 row_ror:2 row_mask:0xf bank_mask:0xf
	v_mov_b32_dpp v63, v55 row_ror:2 row_mask:0xf bank_mask:0xf
	v_mov_b32_dpp v52, v54 row_ror:1 row_mask:0xf bank_mask:0xf
	v_mov_b32_dpp v62, v38 row_shr:2 row_mask:0xf bank_mask:0xf
	v_mov_b32_dpp v53, v55 row_ror:1 row_mask:0xf bank_mask:0xf
	v_mov_b32_dpp v63, v39 row_shr:2 row_mask:0xf bank_mask:0xf
	v_mov_b32_dpp v52, v38 row_shr:1 row_mask:0xf bank_mask:0xf
	v_mov_b32_dpp v53, v39 row_shr:1 row_mask:0xf bank_mask:0xf
	v_pk_fma_f32 v[54:55], v[102:103], v[62:63], v[110:111]
	v_mov_b32_dpp v60, v36 row_shr:2 row_mask:0xf bank_mask:0xf
	v_pk_fma_f32 v[52:53], v[106:107], v[52:53], v[54:55]
	v_mov_b32_dpp v61, v37 row_shr:2 row_mask:0xf bank_mask:0xf
	v_pk_fma_f32 v[52:53], v[38:39], v[98:99], v[52:53]
	v_mov_b32_dpp v58, v36 row_shr:1 row_mask:0xf bank_mask:0xf
	v_mul_f32_e32 v54, 0xbfb8aa3b, v53
	v_exp_f32_e32 v62, v54
	v_mov_b32_dpp v59, v37 row_shr:1 row_mask:0xf bank_mask:0xf
	v_pk_fma_f32 v[54:55], v[100:101], v[60:61], v[108:109]
	s_nop 0
	v_pk_fma_f32 v[54:55], v[104:105], v[58:59], v[54:55]
	v_add_f32_e32 v58, 1.0, v62
	v_rcp_f32_e32 v58, v58
	v_mul_f32_e32 v59, 0xbfb8aa3b, v52
	v_exp_f32_e32 v59, v59
	v_pk_fma_f32 v[54:55], v[36:37], v[96:97], v[54:55]
	v_mul_f32_e32 v53, v53, v58
	v_mul_f32_e32 v47, v47, v53
	v_add_f32_e32 v53, 1.0, v59
	v_mul_f32_e32 v58, 0xbfb8aa3b, v55
	v_rcp_f32_e32 v53, v53
	v_exp_f32_e32 v58, v58
	v_mul_f32_e32 v59, 0xbfb8aa3b, v54
	v_exp_f32_e32 v59, v59
	v_mul_f32_e32 v52, v52, v53
	v_add_f32_e32 v53, 1.0, v58
	v_rcp_f32_e32 v53, v53
	v_add_f32_e32 v58, 1.0, v59
	v_rcp_f32_e32 v58, v58
	v_mul_f32_e32 v46, v46, v52
	v_mul_f32_e32 v52, v55, v53
	v_mul_f32_e32 v45, v45, v52
	v_mul_f32_e32 v52, v54, v58
	v_mul_f32_e32 v44, v44, v52
	v_cvt_pk_bf16_f32 v44, v44, v45
	v_cvt_pk_bf16_f32 v45, v46, v47
	v_mov_b32_dpp v46, v48 row_ror:1 row_mask:0xf bank_mask:0xf
	v_mov_b32_dpp v52, v48 row_ror:2 row_mask:0xf bank_mask:0xf
	v_mov_b32_dpp v47, v49 row_ror:1 row_mask:0xf bank_mask:0xf
	v_mov_b32_dpp v53, v49 row_ror:2 row_mask:0xf bank_mask:0xf
	v_mov_b32_dpp v54, v50 row_ror:2 row_mask:0xf bank_mask:0xf
	v_mov_b32_dpp v55, v51 row_ror:2 row_mask:0xf bank_mask:0xf
	v_mov_b32_dpp v48, v50 row_ror:1 row_mask:0xf bank_mask:0xf
	v_mov_b32_dpp v54, v34 row_shr:2 row_mask:0xf bank_mask:0xf
	v_mov_b32_dpp v49, v51 row_ror:1 row_mask:0xf bank_mask:0xf
	v_mov_b32_dpp v55, v35 row_shr:2 row_mask:0xf bank_mask:0xf
	v_mov_b32_dpp v48, v34 row_shr:1 row_mask:0xf bank_mask:0xf
	v_mov_b32_dpp v49, v35 row_shr:1 row_mask:0xf bank_mask:0xf
	v_pk_fma_f32 v[50:51], v[74:75], v[54:55], v[86:87]
	v_mov_b32_dpp v52, v32 row_shr:2 row_mask:0xf bank_mask:0xf
	v_pk_fma_f32 v[48:49], v[78:79], v[48:49], v[50:51]
	v_mov_b32_dpp v53, v33 row_shr:2 row_mask:0xf bank_mask:0xf
	v_pk_fma_f32 v[48:49], v[34:35], v[70:71], v[48:49]
	v_mov_b32_dpp v46, v32 row_shr:1 row_mask:0xf bank_mask:0xf
	v_mul_f32_e32 v50, 0xbfb8aa3b, v49
	v_exp_f32_e32 v54, v50
	v_mov_b32_dpp v47, v33 row_shr:1 row_mask:0xf bank_mask:0xf
	v_pk_fma_f32 v[50:51], v[72:73], v[52:53], v[84:85]
	s_nop 0
	v_pk_fma_f32 v[46:47], v[76:77], v[46:47], v[50:51]
	v_add_f32_e32 v50, 1.0, v54
	v_rcp_f32_e32 v50, v50
	v_mul_f32_e32 v51, 0xbfb8aa3b, v48
	v_exp_f32_e32 v51, v51
	v_pk_fma_f32 v[46:47], v[32:33], v[68:69], v[46:47]
	v_mul_f32_e32 v49, v49, v50
	v_mul_f32_e32 v43, v43, v49
	v_add_f32_e32 v49, 1.0, v51
	v_mul_f32_e32 v50, 0xbfb8aa3b, v47
	v_mul_f32_e32 v51, 0xbfb8aa3b, v46
	v_rcp_f32_e32 v49, v49
	v_exp_f32_e32 v50, v50
	v_exp_f32_e32 v51, v51
	v_mul_f32_e32 v48, v48, v49
	v_add_f32_e32 v49, 1.0, v50
	v_add_f32_e32 v50, 1.0, v51
	v_rcp_f32_e32 v50, v50
	v_rcp_f32_e32 v49, v49
	v_mul_f32_e32 v42, v42, v48
	v_mul_f32_e32 v46, v46, v50
	v_mul_f32_e32 v47, v47, v49
	v_mul_f32_e32 v40, v40, v46
	v_mul_f32_e32 v41, v41, v47
	v_cvt_pk_bf16_f32 v46, v40, v41
	v_add_u32_e32 v40, 0x90, v205
	v_mad_i64_i32 v[40:41], s[10:11], v40, s82, v[56:57]
	v_lshl_add_u64 v[40:41], v[40:41], 0, v[152:153]
	v_cvt_pk_bf16_f32 v47, v42, v43
	global_store_dwordx4 v[40:41], v[44:47], off
	v_mov_b32_dpp v40, v36 row_ror:1 row_mask:0xf bank_mask:0xf
	v_mov_b32_dpp v42, v36 row_ror:2 row_mask:0xf bank_mask:0xf
	v_mov_b32_dpp v41, v37 row_ror:1 row_mask:0xf bank_mask:0xf
	v_mov_b32_dpp v43, v37 row_ror:2 row_mask:0xf bank_mask:0xf
	v_mov_b32_dpp v44, v38 row_ror:2 row_mask:0xf bank_mask:0xf
	v_mov_b32_dpp v45, v39 row_ror:2 row_mask:0xf bank_mask:0xf
	v_mov_b32_dpp v36, v38 row_ror:1 row_mask:0xf bank_mask:0xf
	v_mov_b32_dpp v44, v22 row_shr:2 row_mask:0xf bank_mask:0xf
	v_mov_b32_dpp v37, v39 row_ror:1 row_mask:0xf bank_mask:0xf
	v_mov_b32_dpp v45, v23 row_shr:2 row_mask:0xf bank_mask:0xf
	v_mov_b32_dpp v36, v22 row_shr:1 row_mask:0xf bank_mask:0xf
	v_mov_b32_dpp v37, v23 row_shr:1 row_mask:0xf bank_mask:0xf
	v_pk_fma_f32 v[38:39], v[102:103], v[44:45], v[110:111]
	v_mov_b32_dpp v42, v20 row_shr:2 row_mask:0xf bank_mask:0xf
	v_pk_fma_f32 v[36:37], v[106:107], v[36:37], v[38:39]
	v_mov_b32_dpp v43, v21 row_shr:2 row_mask:0xf bank_mask:0xf
	v_pk_fma_f32 v[36:37], v[22:23], v[98:99], v[36:37]
	v_mov_b32_dpp v40, v20 row_shr:1 row_mask:0xf bank_mask:0xf
	v_mul_f32_e32 v38, 0xbfb8aa3b, v37
	v_exp_f32_e32 v44, v38
	v_mov_b32_dpp v41, v21 row_shr:1 row_mask:0xf bank_mask:0xf
	v_pk_fma_f32 v[38:39], v[100:101], v[42:43], v[108:109]
	s_nop 0
	v_pk_fma_f32 v[38:39], v[104:105], v[40:41], v[38:39]
	v_add_f32_e32 v40, 1.0, v44
	v_rcp_f32_e32 v40, v40
	v_mul_f32_e32 v41, 0xbfb8aa3b, v36
	v_exp_f32_e32 v41, v41
	v_pk_fma_f32 v[38:39], v[20:21], v[96:97], v[38:39]
	v_mul_f32_e32 v37, v37, v40
	v_mul_f32_e32 v31, v31, v37
	v_add_f32_e32 v37, 1.0, v41
	v_mul_f32_e32 v40, 0xbfb8aa3b, v39
	v_rcp_f32_e32 v37, v37
	v_exp_f32_e32 v40, v40
	v_mul_f32_e32 v41, 0xbfb8aa3b, v38
	v_exp_f32_e32 v41, v41
	v_mul_f32_e32 v36, v36, v37
	v_add_f32_e32 v37, 1.0, v40
	v_rcp_f32_e32 v37, v37
	v_add_f32_e32 v40, 1.0, v41
	v_rcp_f32_e32 v40, v40
	v_mul_f32_e32 v30, v30, v36
	v_mul_f32_e32 v36, v39, v37
	v_mul_f32_e32 v29, v29, v36
	v_mul_f32_e32 v36, v38, v40
	v_mul_f32_e32 v28, v28, v36
	v_cvt_pk_bf16_f32 v28, v28, v29
	v_cvt_pk_bf16_f32 v29, v30, v31
	v_mov_b32_dpp v30, v32 row_ror:1 row_mask:0xf bank_mask:0xf
	v_mov_b32_dpp v36, v32 row_ror:2 row_mask:0xf bank_mask:0xf
	v_mov_b32_dpp v31, v33 row_ror:1 row_mask:0xf bank_mask:0xf
	v_mov_b32_dpp v37, v33 row_ror:2 row_mask:0xf bank_mask:0xf
	v_mov_b32_dpp v38, v34 row_ror:2 row_mask:0xf bank_mask:0xf
	v_mov_b32_dpp v39, v35 row_ror:2 row_mask:0xf bank_mask:0xf
	v_mov_b32_dpp v32, v34 row_ror:1 row_mask:0xf bank_mask:0xf
	v_mov_b32_dpp v38, v14 row_shr:2 row_mask:0xf bank_mask:0xf
	v_mov_b32_dpp v33, v35 row_ror:1 row_mask:0xf bank_mask:0xf
	v_mov_b32_dpp v39, v15 row_shr:2 row_mask:0xf bank_mask:0xf
	v_mov_b32_dpp v32, v14 row_shr:1 row_mask:0xf bank_mask:0xf
	v_mov_b32_dpp v33, v15 row_shr:1 row_mask:0xf bank_mask:0xf
	v_pk_fma_f32 v[34:35], v[74:75], v[38:39], v[86:87]
	v_mov_b32_dpp v36, v12 row_shr:2 row_mask:0xf bank_mask:0xf
	v_pk_fma_f32 v[32:33], v[78:79], v[32:33], v[34:35]
	v_mov_b32_dpp v37, v13 row_shr:2 row_mask:0xf bank_mask:0xf
	v_pk_fma_f32 v[32:33], v[14:15], v[70:71], v[32:33]
	v_mov_b32_dpp v30, v12 row_shr:1 row_mask:0xf bank_mask:0xf
	v_mul_f32_e32 v34, 0xbfb8aa3b, v33
	v_exp_f32_e32 v38, v34
	v_mov_b32_dpp v31, v13 row_shr:1 row_mask:0xf bank_mask:0xf
	v_pk_fma_f32 v[34:35], v[72:73], v[36:37], v[84:85]
	s_nop 0
	v_pk_fma_f32 v[30:31], v[76:77], v[30:31], v[34:35]
	v_add_f32_e32 v34, 1.0, v38
	v_rcp_f32_e32 v34, v34
	v_mul_f32_e32 v35, 0xbfb8aa3b, v32
	v_exp_f32_e32 v35, v35
	v_pk_fma_f32 v[30:31], v[12:13], v[68:69], v[30:31]
	v_mul_f32_e32 v33, v33, v34
	v_mul_f32_e32 v27, v27, v33
	v_add_f32_e32 v33, 1.0, v35
	v_mul_f32_e32 v34, 0xbfb8aa3b, v31
	v_mul_f32_e32 v35, 0xbfb8aa3b, v30
	v_rcp_f32_e32 v33, v33
	v_exp_f32_e32 v34, v34
	v_exp_f32_e32 v35, v35
	v_mul_f32_e32 v32, v32, v33
	v_add_f32_e32 v33, 1.0, v34
	v_add_f32_e32 v34, 1.0, v35
	v_rcp_f32_e32 v34, v34
	v_rcp_f32_e32 v33, v33
	v_mul_f32_e32 v26, v26, v32
	v_mul_f32_e32 v30, v30, v34
	v_mul_f32_e32 v31, v31, v33
	v_mul_f32_e32 v24, v24, v30
	v_mul_f32_e32 v25, v25, v31
	v_cvt_pk_bf16_f32 v30, v24, v25
	v_add_u32_e32 v24, 0xa0, v205
	v_mad_i64_i32 v[24:25], s[10:11], v24, s82, v[56:57]
	v_lshl_add_u64 v[24:25], v[24:25], 0, v[152:153]
	v_cvt_pk_bf16_f32 v31, v26, v27
	global_store_dwordx4 v[24:25], v[28:31], off
	v_mov_b32_dpp v24, v20 row_ror:1 row_mask:0xf bank_mask:0xf
	v_mov_b32_dpp v26, v20 row_ror:2 row_mask:0xf bank_mask:0xf
	v_mov_b32_dpp v25, v21 row_ror:1 row_mask:0xf bank_mask:0xf
	v_mov_b32_dpp v27, v21 row_ror:2 row_mask:0xf bank_mask:0xf
	v_mov_b32_dpp v28, v22 row_ror:2 row_mask:0xf bank_mask:0xf
	v_mov_b32_dpp v29, v23 row_ror:2 row_mask:0xf bank_mask:0xf
	v_mov_b32_dpp v20, v22 row_ror:1 row_mask:0xf bank_mask:0xf
	v_mov_b32_dpp v28, v18 row_shr:2 row_mask:0xf bank_mask:0xf
	v_mov_b32_dpp v21, v23 row_ror:1 row_mask:0xf bank_mask:0xf
	v_mov_b32_dpp v29, v19 row_shr:2 row_mask:0xf bank_mask:0xf
	v_mov_b32_dpp v20, v18 row_shr:1 row_mask:0xf bank_mask:0xf
	v_mov_b32_dpp v21, v19 row_shr:1 row_mask:0xf bank_mask:0xf
	v_pk_fma_f32 v[22:23], v[102:103], v[28:29], v[110:111]
	v_mov_b32_dpp v26, v16 row_shr:2 row_mask:0xf bank_mask:0xf
	v_pk_fma_f32 v[20:21], v[106:107], v[20:21], v[22:23]
	v_mov_b32_dpp v27, v17 row_shr:2 row_mask:0xf bank_mask:0xf
	v_pk_fma_f32 v[18:19], v[18:19], v[98:99], v[20:21]
	v_mov_b32_dpp v24, v16 row_shr:1 row_mask:0xf bank_mask:0xf
	v_mul_f32_e32 v20, 0xbfb8aa3b, v19
	v_exp_f32_e32 v22, v20
	v_mul_f32_e32 v23, 0xbfb8aa3b, v18
	v_exp_f32_e32 v23, v23
	v_mov_b32_dpp v25, v17 row_shr:1 row_mask:0xf bank_mask:0xf
	v_add_f32_e32 v22, 1.0, v22
	v_rcp_f32_e32 v22, v22
	v_pk_fma_f32 v[20:21], v[100:101], v[26:27], v[108:109]
	v_mul_f32_e32 v19, v19, v22
	v_pk_fma_f32 v[20:21], v[104:105], v[24:25], v[20:21]
	v_mul_f32_e32 v11, v11, v19
	v_pk_fma_f32 v[16:17], v[16:17], v[96:97], v[20:21]
	v_add_f32_e32 v19, 1.0, v23
	v_mul_f32_e32 v20, 0xbfb8aa3b, v17
	v_mul_f32_e32 v21, 0xbfb8aa3b, v16
	v_rcp_f32_e32 v19, v19
	v_exp_f32_e32 v20, v20
	v_exp_f32_e32 v21, v21
	v_mul_f32_e32 v18, v18, v19
	v_add_f32_e32 v19, 1.0, v20
	v_add_f32_e32 v20, 1.0, v21
	v_rcp_f32_e32 v19, v19
	v_rcp_f32_e32 v20, v20
	v_mul_f32_e32 v10, v10, v18
	v_mul_f32_e32 v17, v17, v19
	v_mul_f32_e32 v16, v16, v20
	v_mul_f32_e32 v9, v9, v17
	v_mul_f32_e32 v8, v8, v16
	v_cvt_pk_bf16_f32 v8, v8, v9
	v_cvt_pk_bf16_f32 v9, v10, v11
	v_mov_b32_dpp v10, v12 row_ror:1 row_mask:0xf bank_mask:0xf
	v_mov_b32_dpp v16, v12 row_ror:2 row_mask:0xf bank_mask:0xf
	v_mov_b32_dpp v11, v13 row_ror:1 row_mask:0xf bank_mask:0xf
	v_mov_b32_dpp v17, v13 row_ror:2 row_mask:0xf bank_mask:0xf
	v_mov_b32_dpp v18, v14 row_ror:2 row_mask:0xf bank_mask:0xf
	v_mov_b32_dpp v19, v15 row_ror:2 row_mask:0xf bank_mask:0xf
	v_mov_b32_dpp v12, v14 row_ror:1 row_mask:0xf bank_mask:0xf
	v_mov_b32_dpp v18, v6 row_shr:2 row_mask:0xf bank_mask:0xf
	v_mov_b32_dpp v13, v15 row_ror:1 row_mask:0xf bank_mask:0xf
	v_mov_b32_dpp v19, v7 row_shr:2 row_mask:0xf bank_mask:0xf
	v_mov_b32_dpp v12, v6 row_shr:1 row_mask:0xf bank_mask:0xf
	v_mov_b32_dpp v13, v7 row_shr:1 row_mask:0xf bank_mask:0xf
	v_pk_fma_f32 v[14:15], v[74:75], v[18:19], v[86:87]
	v_mov_b32_dpp v16, v4 row_shr:2 row_mask:0xf bank_mask:0xf
	v_pk_fma_f32 v[12:13], v[78:79], v[12:13], v[14:15]
	v_mov_b32_dpp v17, v5 row_shr:2 row_mask:0xf bank_mask:0xf
	v_pk_fma_f32 v[6:7], v[6:7], v[70:71], v[12:13]
	v_mov_b32_dpp v10, v4 row_shr:1 row_mask:0xf bank_mask:0xf
	v_mul_f32_e32 v12, 0xbfb8aa3b, v7
	v_exp_f32_e32 v14, v12
	v_mov_b32_dpp v11, v5 row_shr:1 row_mask:0xf bank_mask:0xf
	v_pk_fma_f32 v[12:13], v[72:73], v[16:17], v[84:85]
	s_nop 0
	v_pk_fma_f32 v[10:11], v[76:77], v[10:11], v[12:13]
	v_add_f32_e32 v12, 1.0, v14
	v_rcp_f32_e32 v12, v12
	v_mul_f32_e32 v13, 0xbfb8aa3b, v6
	v_exp_f32_e32 v13, v13
	v_pk_fma_f32 v[4:5], v[4:5], v[68:69], v[10:11]
	v_mul_f32_e32 v7, v7, v12
	v_mul_f32_e32 v3, v3, v7
	v_add_f32_e32 v7, 1.0, v13
	v_mul_f32_e32 v10, 0xbfb8aa3b, v5
	v_mul_f32_e32 v11, 0xbfb8aa3b, v4
	v_rcp_f32_e32 v7, v7
	v_exp_f32_e32 v10, v10
	v_exp_f32_e32 v11, v11
	v_mul_f32_e32 v6, v6, v7
	v_add_f32_e32 v7, 1.0, v10
	v_add_f32_e32 v10, 1.0, v11
	v_rcp_f32_e32 v10, v10
	v_rcp_f32_e32 v7, v7
	v_mul_f32_e32 v2, v2, v6
	v_mul_f32_e32 v4, v4, v10
	v_mul_f32_e32 v5, v5, v7
	v_mul_f32_e32 v0, v0, v4
	v_mul_f32_e32 v1, v1, v5
	v_cvt_pk_bf16_f32 v10, v0, v1
	v_add_u32_e32 v0, 0xb0, v205
	v_mad_i64_i32 v[0:1], s[10:11], v0, s82, v[56:57]
	v_lshl_add_u64 v[0:1], v[0:1], 0, v[152:153]
	v_cvt_pk_bf16_f32 v11, v2, v3
	global_store_dwordx4 v[0:1], v[8:11], off
	s_waitcnt lgkmcnt(0)
	s_barrier
	s_cbranch_vccnz .LBB0_1479
	s_andn2_b64 vcc, exec, s[16:17]
	s_cbranch_vccnz .LBB0_1478
	s_barrier
	s_branch .LBB0_1478

.LBB0_1583:
	s_add_u32 s65, s40, 0x100
	v_mov_b32_e32 v0, 0
	s_addc_u32 s66, s41, 0
	s_mov_b32 s67, -2
	v_mov_b32_e32 v1, v0
	v_mov_b32_e32 v2, v0
	v_mov_b32_e32 v3, v0
	v_mov_b32_e32 v4, v0
	v_mov_b32_e32 v5, v0
	v_mov_b32_e32 v6, v0
	v_mov_b32_e32 v7, v0
	v_mov_b32_e32 v16, v0
	v_mov_b32_e32 v17, v0
	v_mov_b32_e32 v18, v0
	v_mov_b32_e32 v19, v0
	v_mov_b32_e32 v20, v0
	v_mov_b32_e32 v21, v0
	v_mov_b32_e32 v22, v0
	v_mov_b32_e32 v23, v0
	v_mov_b32_e32 v32, v0
	v_mov_b32_e32 v33, v0
	v_mov_b32_e32 v34, v0
	v_mov_b32_e32 v35, v0
	v_mov_b32_e32 v36, v0
	v_mov_b32_e32 v37, v0
	v_mov_b32_e32 v38, v0
	v_mov_b32_e32 v39, v0
	v_mov_b32_e32 v48, v0
	v_mov_b32_e32 v49, v0
	v_mov_b32_e32 v50, v0
	v_mov_b32_e32 v51, v0
	v_mov_b32_e32 v52, v0
	v_mov_b32_e32 v53, v0
	v_mov_b32_e32 v54, v0
	v_mov_b32_e32 v55, v0
	v_mov_b32_e32 v8, v0
	v_mov_b32_e32 v9, v0
	v_mov_b32_e32 v10, v0
	v_mov_b32_e32 v11, v0
	v_mov_b32_e32 v12, v0
	v_mov_b32_e32 v13, v0
	v_mov_b32_e32 v14, v0
	v_mov_b32_e32 v15, v0
	v_mov_b32_e32 v24, v0
	v_mov_b32_e32 v25, v0
	v_mov_b32_e32 v26, v0
	v_mov_b32_e32 v27, v0
	v_mov_b32_e32 v28, v0
	v_mov_b32_e32 v29, v0
	v_mov_b32_e32 v30, v0
	v_mov_b32_e32 v31, v0
	v_mov_b32_e32 v40, v0
	v_mov_b32_e32 v41, v0
	v_mov_b32_e32 v42, v0
	v_mov_b32_e32 v43, v0
	v_mov_b32_e32 v44, v0
	v_mov_b32_e32 v45, v0
	v_mov_b32_e32 v46, v0
	v_mov_b32_e32 v47, v0
	v_mov_b32_e32 v56, v0
	v_mov_b32_e32 v57, v0
	v_mov_b32_e32 v58, v0
	v_mov_b32_e32 v59, v0
	v_mov_b32_e32 v60, v0
	v_mov_b32_e32 v61, v0
	v_mov_b32_e32 v62, v0
	v_mov_b32_e32 v63, v0
	v_mov_b32_e32 v64, v0
	v_mov_b32_e32 v65, v0
	v_mov_b32_e32 v66, v0
	v_mov_b32_e32 v67, v0
	v_mov_b32_e32 v68, v0
	v_mov_b32_e32 v69, v0
	v_mov_b32_e32 v70, v0
	v_mov_b32_e32 v71, v0
	v_mov_b32_e32 v80, v0
	v_mov_b32_e32 v81, v0
	v_mov_b32_e32 v82, v0
	v_mov_b32_e32 v83, v0
	v_mov_b32_e32 v84, v0
	v_mov_b32_e32 v85, v0
	v_mov_b32_e32 v86, v0
	v_mov_b32_e32 v87, v0
	v_mov_b32_e32 v96, v0
	v_mov_b32_e32 v97, v0
	v_mov_b32_e32 v98, v0
	v_mov_b32_e32 v99, v0
	v_mov_b32_e32 v100, v0
	v_mov_b32_e32 v101, v0
	v_mov_b32_e32 v102, v0
	v_mov_b32_e32 v103, v0
	v_mov_b32_e32 v112, v0
	v_mov_b32_e32 v113, v0
	v_mov_b32_e32 v114, v0
	v_mov_b32_e32 v115, v0
	v_mov_b32_e32 v116, v0
	v_mov_b32_e32 v117, v0
	v_mov_b32_e32 v118, v0
	v_mov_b32_e32 v119, v0
	v_mov_b32_e32 v72, v0
	v_mov_b32_e32 v73, v0
	v_mov_b32_e32 v74, v0
	v_mov_b32_e32 v75, v0
	v_mov_b32_e32 v76, v0
	v_mov_b32_e32 v77, v0
	v_mov_b32_e32 v78, v0
	v_mov_b32_e32 v79, v0
	v_mov_b32_e32 v88, v0
	v_mov_b32_e32 v89, v0
	v_mov_b32_e32 v90, v0
	v_mov_b32_e32 v91, v0
	v_mov_b32_e32 v92, v0
	v_mov_b32_e32 v93, v0
	v_mov_b32_e32 v94, v0
	v_mov_b32_e32 v95, v0
	v_mov_b32_e32 v104, v0
	v_mov_b32_e32 v105, v0
	v_mov_b32_e32 v106, v0
	v_mov_b32_e32 v107, v0
	v_mov_b32_e32 v108, v0
	v_mov_b32_e32 v109, v0
	v_mov_b32_e32 v110, v0
	v_mov_b32_e32 v111, v0
	v_mov_b32_e32 v120, v0
	v_mov_b32_e32 v121, v0
	v_mov_b32_e32 v122, v0
	v_mov_b32_e32 v123, v0
	v_mov_b32_e32 v124, v0
	v_mov_b32_e32 v125, v0
	v_mov_b32_e32 v126, v0
	v_mov_b32_e32 v127, v0
	s_nop 0
	s_nop 0
	s_nop 0
.LBB0_1584:
	ds_read_b128 v[144:147], v154
	ds_read_b128 v[158:161], v154 offset:1024
	ds_read_b128 v[162:165], v154 offset:2048
	ds_read_b128 v[166:169], v154 offset:3072
	ds_read_b128 v[170:173], v155
	ds_read_b128 v[174:177], v155 offset:1024
	ds_read_b128 v[178:181], v155 offset:2048
	ds_read_b128 v[182:185], v155 offset:3072
	s_add_u32 s40, s30, 0x100
	s_addc_u32 s41, s31, 0
	s_cmp_eq_u32 s67, 40
	s_cselect_b32 s53, s9, s41
	s_cselect_b32 s52, s8, s40
	s_cselect_b32 s43, s29, s66
	s_cselect_b32 s42, s28, s65
	v_lshl_add_u64 v[148:149], s[30:31], 0, v[136:137]
	s_add_i32 m0, s50, 0xc000
	ds_read_b128 v[186:189], v156
	ds_read_b128 v[190:193], v156 offset:1024
	ds_read_b128 v[198:201], v156 offset:2048
	ds_read_b128 v[202:205], v156 offset:3072
	ds_read_b128 v[206:209], v156 offset:4096
	ds_read_b128 v[210:213], v156 offset:5120
	ds_read_b128 v[214:217], v156 offset:6144
	ds_read_b128 v[218:221], v156 offset:7168
	global_load_lds_dwordx4 v[148:149], off
	v_lshl_add_u64 v[148:149], s[30:31], 0, v[138:139]
	s_add_i32 m0, s50, 0xe000
	s_nop 0
	global_load_lds_dwordx4 v[148:149], off
	s_waitcnt vmcnt(8)
	s_waitcnt lgkmcnt(0)
	s_barrier
	s_setprio 1
	s_waitcnt lgkmcnt(0)
	v_mfma_f32_16x16x32_bf16 v[124:127], v[144:147], v[186:189], v[124:127]
	v_mfma_f32_16x16x32_bf16 v[120:123], v[162:165], v[186:189], v[120:123]
	v_mfma_f32_16x16x32_bf16 v[108:111], v[144:147], v[198:201], v[108:111]
	v_mfma_f32_16x16x32_bf16 v[104:107], v[162:165], v[198:201], v[104:107]
	v_mfma_f32_16x16x32_bf16 v[92:95], v[144:147], v[206:209], v[92:95]
	v_mfma_f32_16x16x32_bf16 v[88:91], v[162:165], v[206:209], v[88:91]
	v_mfma_f32_16x16x32_bf16 v[76:79], v[144:147], v[214:217], v[76:79]
	v_mfma_f32_16x16x32_bf16 v[72:75], v[162:165], v[214:217], v[72:75]
	v_mfma_f32_16x16x32_bf16 v[124:127], v[158:161], v[190:193], v[124:127]
	v_mfma_f32_16x16x32_bf16 v[120:123], v[166:169], v[190:193], v[120:123]
	v_mfma_f32_16x16x32_bf16 v[108:111], v[158:161], v[202:205], v[108:111]
	v_mfma_f32_16x16x32_bf16 v[104:107], v[166:169], v[202:205], v[104:107]
	v_mfma_f32_16x16x32_bf16 v[92:95], v[158:161], v[210:213], v[92:95]
	v_mfma_f32_16x16x32_bf16 v[88:91], v[166:169], v[210:213], v[88:91]
	v_mfma_f32_16x16x32_bf16 v[76:79], v[158:161], v[218:221], v[76:79]
	v_mfma_f32_16x16x32_bf16 v[72:75], v[166:169], v[218:221], v[72:75]
	s_setprio 0
	s_setprio 1
	v_mfma_f32_16x16x32_bf16 v[116:119], v[170:173], v[186:189], v[116:119]
	v_mfma_f32_16x16x32_bf16 v[112:115], v[178:181], v[186:189], v[112:115]
	v_mfma_f32_16x16x32_bf16 v[100:103], v[170:173], v[198:201], v[100:103]
	v_mfma_f32_16x16x32_bf16 v[96:99], v[178:181], v[198:201], v[96:99]
	v_mfma_f32_16x16x32_bf16 v[84:87], v[170:173], v[206:209], v[84:87]
	v_mfma_f32_16x16x32_bf16 v[80:83], v[178:181], v[206:209], v[80:83]
	v_mfma_f32_16x16x32_bf16 v[68:71], v[170:173], v[214:217], v[68:71]
	v_mfma_f32_16x16x32_bf16 v[64:67], v[178:181], v[214:217], v[64:67]
	v_mfma_f32_16x16x32_bf16 v[116:119], v[174:177], v[190:193], v[116:119]
	v_mfma_f32_16x16x32_bf16 v[112:115], v[182:185], v[190:193], v[112:115]
	v_mfma_f32_16x16x32_bf16 v[100:103], v[174:177], v[202:205], v[100:103]
	v_mfma_f32_16x16x32_bf16 v[96:99], v[182:185], v[202:205], v[96:99]
	v_mfma_f32_16x16x32_bf16 v[84:87], v[174:177], v[210:213], v[84:87]
	v_mfma_f32_16x16x32_bf16 v[80:83], v[182:185], v[210:213], v[80:83]
	v_mfma_f32_16x16x32_bf16 v[68:71], v[174:177], v[218:221], v[68:71]
	v_mfma_f32_16x16x32_bf16 v[64:67], v[182:185], v[218:221], v[64:67]
	s_setprio 0
	s_barrier
	s_add_i32 s30, s60, s3
	v_lshl_add_u64 v[148:149], s[42:43], 0, v[132:133]
	s_mov_b32 m0, s30
	ds_read_b128 v[186:189], v156 offset:16384
	ds_read_b128 v[190:193], v156 offset:17408
	ds_read_b128 v[198:201], v156 offset:18432
	ds_read_b128 v[202:205], v156 offset:19456
	ds_read_b128 v[206:209], v156 offset:20480
	ds_read_b128 v[210:213], v156 offset:21504
	ds_read_b128 v[214:217], v156 offset:22528
	ds_read_b128 v[218:221], v156 offset:23552
	global_load_lds_dwordx4 v[148:149], off
	s_add_i32 m0, s30, 0x2000
	s_add_u32 s30, s42, 0xb0000
	v_lshl_add_u64 v[194:195], s[42:43], 0, v[128:129]
	s_addc_u32 s31, s43, 0
	s_add_i32 s46, s61, s3
	global_load_lds_dwordx4 v[194:195], off
	v_lshl_add_u64 v[196:197], s[30:31], 0, v[132:133]
	s_mov_b32 m0, s46
	v_lshl_add_u64 v[222:223], s[52:53], 0, v[130:131]
	global_load_lds_dwordx4 v[196:197], off
	v_lshl_add_u64 v[196:197], s[30:31], 0, v[128:129]
	s_add_i32 m0, s46, 0x2000
	s_nop 0
	global_load_lds_dwordx4 v[196:197], off
	v_lshl_add_u64 v[196:197], s[52:53], 0, v[134:135]
	s_mov_b32 m0, s50
	s_nop 0
	global_load_lds_dwordx4 v[196:197], off
	s_mov_b32 m0, s51
	s_nop 0
	global_load_lds_dwordx4 v[222:223], off
	s_nop 0
	s_waitcnt vmcnt(8)
	s_waitcnt lgkmcnt(0)
	s_barrier
	s_setprio 1
	s_waitcnt lgkmcnt(0)
	v_mfma_f32_16x16x32_bf16 v[60:63], v[144:147], v[186:189], v[60:63]
	v_mfma_f32_16x16x32_bf16 v[56:59], v[162:165], v[186:189], v[56:59]
	v_mfma_f32_16x16x32_bf16 v[44:47], v[144:147], v[198:201], v[44:47]
	v_mfma_f32_16x16x32_bf16 v[40:43], v[162:165], v[198:201], v[40:43]
	v_mfma_f32_16x16x32_bf16 v[28:31], v[144:147], v[206:209], v[28:31]
	v_mfma_f32_16x16x32_bf16 v[24:27], v[162:165], v[206:209], v[24:27]
	v_mfma_f32_16x16x32_bf16 v[12:15], v[144:147], v[214:217], v[12:15]
	v_mfma_f32_16x16x32_bf16 v[8:11], v[162:165], v[214:217], v[8:11]
	v_mfma_f32_16x16x32_bf16 v[60:63], v[158:161], v[190:193], v[60:63]
	v_mfma_f32_16x16x32_bf16 v[56:59], v[166:169], v[190:193], v[56:59]
	v_mfma_f32_16x16x32_bf16 v[44:47], v[158:161], v[202:205], v[44:47]
	v_mfma_f32_16x16x32_bf16 v[40:43], v[166:169], v[202:205], v[40:43]
	v_mfma_f32_16x16x32_bf16 v[28:31], v[158:161], v[210:213], v[28:31]
	v_mfma_f32_16x16x32_bf16 v[24:27], v[166:169], v[210:213], v[24:27]
	v_mfma_f32_16x16x32_bf16 v[12:15], v[158:161], v[218:221], v[12:15]
	v_mfma_f32_16x16x32_bf16 v[8:11], v[166:169], v[218:221], v[8:11]
	s_setprio 0
	s_setprio 1
	v_mfma_f32_16x16x32_bf16 v[52:55], v[170:173], v[186:189], v[52:55]
	v_mfma_f32_16x16x32_bf16 v[48:51], v[178:181], v[186:189], v[48:51]
	v_mfma_f32_16x16x32_bf16 v[36:39], v[170:173], v[198:201], v[36:39]
	v_mfma_f32_16x16x32_bf16 v[32:35], v[178:181], v[198:201], v[32:35]
	v_mfma_f32_16x16x32_bf16 v[20:23], v[170:173], v[206:209], v[20:23]
	v_mfma_f32_16x16x32_bf16 v[16:19], v[178:181], v[206:209], v[16:19]
	v_mfma_f32_16x16x32_bf16 v[4:7], v[170:173], v[214:217], v[4:7]
	v_mfma_f32_16x16x32_bf16 v[0:3], v[178:181], v[214:217], v[0:3]
	v_mfma_f32_16x16x32_bf16 v[52:55], v[174:177], v[190:193], v[52:55]
	v_mfma_f32_16x16x32_bf16 v[48:51], v[182:185], v[190:193], v[48:51]
	v_mfma_f32_16x16x32_bf16 v[36:39], v[174:177], v[202:205], v[36:39]
	v_mfma_f32_16x16x32_bf16 v[32:35], v[182:185], v[202:205], v[32:35]
	v_mfma_f32_16x16x32_bf16 v[20:23], v[174:177], v[210:213], v[20:23]
	v_mfma_f32_16x16x32_bf16 v[16:19], v[182:185], v[210:213], v[16:19]
	v_mfma_f32_16x16x32_bf16 v[4:7], v[174:177], v[218:221], v[4:7]
	v_mfma_f32_16x16x32_bf16 v[0:3], v[182:185], v[218:221], v[0:3]
	s_setprio 0
	s_barrier
	s_add_i32 s46, 0, 0x18000
	v_add_u32_e32 v157, s46, v152
	s_add_i32 s47, 0, 0x1c000
	ds_read_b128 v[144:147], v157
	ds_read_b128 v[158:161], v157 offset:1024
	ds_read_b128 v[162:165], v157 offset:2048
	ds_read_b128 v[166:169], v157 offset:3072
	v_add_u32_e32 v157, s47, v152
	ds_read_b128 v[170:173], v157
	ds_read_b128 v[174:177], v157 offset:1024
	ds_read_b128 v[178:181], v157 offset:2048
	ds_read_b128 v[182:185], v157 offset:3072
	s_add_u32 s30, s52, 0xb0000
	s_addc_u32 s31, s53, 0
	s_mov_b32 m0, s54
	v_lshl_add_u64 v[224:225], s[30:31], 0, v[134:135]
	ds_read_b128 v[186:189], v156 offset:32768
	ds_read_b128 v[190:193], v156 offset:33792
	ds_read_b128 v[198:201], v156 offset:34816
	ds_read_b128 v[202:205], v156 offset:35840
	ds_read_b128 v[206:209], v156 offset:36864
	ds_read_b128 v[210:213], v156 offset:37888
	ds_read_b128 v[214:217], v156 offset:38912
	ds_read_b128 v[218:221], v156 offset:39936
	global_load_lds_dwordx4 v[224:225], off
	v_lshl_add_u64 v[224:225], s[30:31], 0, v[130:131]
	s_mov_b32 m0, s55
	s_nop 0
	global_load_lds_dwordx4 v[224:225], off
	s_nop 0
	s_waitcnt vmcnt(8)
	s_waitcnt lgkmcnt(0)
	s_barrier
	s_setprio 1
	s_waitcnt lgkmcnt(0)
	v_mfma_f32_16x16x32_bf16 v[124:127], v[144:147], v[186:189], v[124:127]
	v_mfma_f32_16x16x32_bf16 v[120:123], v[162:165], v[186:189], v[120:123]
	v_mfma_f32_16x16x32_bf16 v[108:111], v[144:147], v[198:201], v[108:111]
	v_mfma_f32_16x16x32_bf16 v[104:107], v[162:165], v[198:201], v[104:107]
	v_mfma_f32_16x16x32_bf16 v[92:95], v[144:147], v[206:209], v[92:95]
	v_mfma_f32_16x16x32_bf16 v[88:91], v[162:165], v[206:209], v[88:91]
	v_mfma_f32_16x16x32_bf16 v[76:79], v[144:147], v[214:217], v[76:79]
	v_mfma_f32_16x16x32_bf16 v[72:75], v[162:165], v[214:217], v[72:75]
	v_mfma_f32_16x16x32_bf16 v[124:127], v[158:161], v[190:193], v[124:127]
	v_mfma_f32_16x16x32_bf16 v[120:123], v[166:169], v[190:193], v[120:123]
	v_mfma_f32_16x16x32_bf16 v[108:111], v[158:161], v[202:205], v[108:111]
	v_mfma_f32_16x16x32_bf16 v[104:107], v[166:169], v[202:205], v[104:107]
	v_mfma_f32_16x16x32_bf16 v[92:95], v[158:161], v[210:213], v[92:95]
	v_mfma_f32_16x16x32_bf16 v[88:91], v[166:169], v[210:213], v[88:91]
	v_mfma_f32_16x16x32_bf16 v[76:79], v[158:161], v[218:221], v[76:79]
	v_mfma_f32_16x16x32_bf16 v[72:75], v[166:169], v[218:221], v[72:75]
	s_setprio 0
	s_setprio 1
	v_mfma_f32_16x16x32_bf16 v[116:119], v[170:173], v[186:189], v[116:119]
	v_mfma_f32_16x16x32_bf16 v[112:115], v[178:181], v[186:189], v[112:115]
	v_mfma_f32_16x16x32_bf16 v[100:103], v[170:173], v[198:201], v[100:103]
	v_mfma_f32_16x16x32_bf16 v[96:99], v[178:181], v[198:201], v[96:99]
	v_mfma_f32_16x16x32_bf16 v[84:87], v[170:173], v[206:209], v[84:87]
	v_mfma_f32_16x16x32_bf16 v[80:83], v[178:181], v[206:209], v[80:83]
	v_mfma_f32_16x16x32_bf16 v[68:71], v[170:173], v[214:217], v[68:71]
	v_mfma_f32_16x16x32_bf16 v[64:67], v[178:181], v[214:217], v[64:67]
	v_mfma_f32_16x16x32_bf16 v[116:119], v[174:177], v[190:193], v[116:119]
	v_mfma_f32_16x16x32_bf16 v[112:115], v[182:185], v[190:193], v[112:115]
	v_mfma_f32_16x16x32_bf16 v[100:103], v[174:177], v[202:205], v[100:103]
	v_mfma_f32_16x16x32_bf16 v[96:99], v[182:185], v[202:205], v[96:99]
	v_mfma_f32_16x16x32_bf16 v[84:87], v[174:177], v[210:213], v[84:87]
	v_mfma_f32_16x16x32_bf16 v[80:83], v[182:185], v[210:213], v[80:83]
	v_mfma_f32_16x16x32_bf16 v[68:71], v[174:177], v[218:221], v[68:71]
	v_mfma_f32_16x16x32_bf16 v[64:67], v[182:185], v[218:221], v[64:67]
	s_setprio 0
	s_barrier
	s_add_i32 s30, s46, s3
	v_lshl_add_u64 v[148:149], v[148:149], 0, s[16:17]
	s_mov_b32 m0, s30
	ds_read_b128 v[186:189], v156 offset:49152
	ds_read_b128 v[190:193], v156 offset:50176
	ds_read_b128 v[198:201], v156 offset:51200
	ds_read_b128 v[202:205], v156 offset:52224
	ds_read_b128 v[206:209], v156 offset:53248
	ds_read_b128 v[210:213], v156 offset:54272
	ds_read_b128 v[214:217], v156 offset:55296
	ds_read_b128 v[218:221], v156 offset:56320
	global_load_lds_dwordx4 v[148:149], off
	s_add_i32 m0, s30, 0x2000
	s_add_u32 s30, s42, 0xb0080
	v_lshl_add_u64 v[148:149], v[194:195], 0, s[16:17]
	s_addc_u32 s31, s43, 0
	s_add_i32 s42, s47, s3
	global_load_lds_dwordx4 v[148:149], off
	v_lshl_add_u64 v[148:149], s[30:31], 0, v[132:133]
	s_mov_b32 m0, s42
	s_nop 0
	global_load_lds_dwordx4 v[148:149], off
	v_lshl_add_u64 v[148:149], s[30:31], 0, v[128:129]
	s_add_i32 m0, s42, 0x2000
	s_nop 0
	global_load_lds_dwordx4 v[148:149], off
	v_lshl_add_u64 v[148:149], v[196:197], 0, s[16:17]
	s_mov_b32 m0, s57
	s_nop 0
	global_load_lds_dwordx4 v[148:149], off
	v_lshl_add_u64 v[148:149], v[222:223], 0, s[16:17]
	s_mov_b32 m0, s58
	s_nop 0
	global_load_lds_dwordx4 v[148:149], off
	s_waitcnt vmcnt(8)
	s_waitcnt lgkmcnt(0)
	s_barrier
	s_setprio 1
	s_waitcnt lgkmcnt(0)
	v_mfma_f32_16x16x32_bf16 v[60:63], v[144:147], v[186:189], v[60:63]
	v_mfma_f32_16x16x32_bf16 v[56:59], v[162:165], v[186:189], v[56:59]
	v_mfma_f32_16x16x32_bf16 v[44:47], v[144:147], v[198:201], v[44:47]
	v_mfma_f32_16x16x32_bf16 v[40:43], v[162:165], v[198:201], v[40:43]
	v_mfma_f32_16x16x32_bf16 v[28:31], v[144:147], v[206:209], v[28:31]
	v_mfma_f32_16x16x32_bf16 v[24:27], v[162:165], v[206:209], v[24:27]
	v_mfma_f32_16x16x32_bf16 v[12:15], v[144:147], v[214:217], v[12:15]
	v_mfma_f32_16x16x32_bf16 v[8:11], v[162:165], v[214:217], v[8:11]
	v_mfma_f32_16x16x32_bf16 v[60:63], v[158:161], v[190:193], v[60:63]
	v_mfma_f32_16x16x32_bf16 v[56:59], v[166:169], v[190:193], v[56:59]
	v_mfma_f32_16x16x32_bf16 v[44:47], v[158:161], v[202:205], v[44:47]
	v_mfma_f32_16x16x32_bf16 v[40:43], v[166:169], v[202:205], v[40:43]
	v_mfma_f32_16x16x32_bf16 v[28:31], v[158:161], v[210:213], v[28:31]
	v_mfma_f32_16x16x32_bf16 v[24:27], v[166:169], v[210:213], v[24:27]
	v_mfma_f32_16x16x32_bf16 v[12:15], v[158:161], v[218:221], v[12:15]
	v_mfma_f32_16x16x32_bf16 v[8:11], v[166:169], v[218:221], v[8:11]
	s_setprio 0
	s_setprio 1
	v_mfma_f32_16x16x32_bf16 v[52:55], v[170:173], v[186:189], v[52:55]
	v_mfma_f32_16x16x32_bf16 v[48:51], v[178:181], v[186:189], v[48:51]
	v_mfma_f32_16x16x32_bf16 v[36:39], v[170:173], v[198:201], v[36:39]
	v_mfma_f32_16x16x32_bf16 v[32:35], v[178:181], v[198:201], v[32:35]
	v_mfma_f32_16x16x32_bf16 v[20:23], v[170:173], v[206:209], v[20:23]
	v_mfma_f32_16x16x32_bf16 v[16:19], v[178:181], v[206:209], v[16:19]
	v_mfma_f32_16x16x32_bf16 v[4:7], v[170:173], v[214:217], v[4:7]
	v_mfma_f32_16x16x32_bf16 v[0:3], v[178:181], v[214:217], v[0:3]
	v_mfma_f32_16x16x32_bf16 v[52:55], v[174:177], v[190:193], v[52:55]
	v_mfma_f32_16x16x32_bf16 v[48:51], v[182:185], v[190:193], v[48:51]
	v_mfma_f32_16x16x32_bf16 v[36:39], v[174:177], v[202:205], v[36:39]
	v_mfma_f32_16x16x32_bf16 v[32:35], v[182:185], v[202:205], v[32:35]
	v_mfma_f32_16x16x32_bf16 v[20:23], v[174:177], v[210:213], v[20:23]
	v_mfma_f32_16x16x32_bf16 v[16:19], v[182:185], v[210:213], v[16:19]
	v_mfma_f32_16x16x32_bf16 v[4:7], v[174:177], v[218:221], v[4:7]
	v_mfma_f32_16x16x32_bf16 v[0:3], v[182:185], v[218:221], v[0:3]
	s_setprio 0
	s_barrier
	s_add_i32 s67, s67, 2
	s_add_u32 s65, s65, 0x100
	s_addc_u32 s66, s66, 0
	s_cmp_gt_u32 s67, 41
	s_mov_b64 s[30:31], s[40:41]
	s_cbranch_scc0 .LBB0_1584
	s_and_b64 vcc, exec, s[18:19]
	s_cbranch_vccz .LBB0_1587
	s_barrier
